# mixer lists: small diff units appended to the stage-0 list (one 88-item list per XCD, stage-1 list empty), removes one low-utilisation stage and its transition
# speedup vs baseline: 1.0168x; 1.0108x over previous
.LBB0_416:
	s_cmp_lg_u32 s10, 0
	s_cselect_b64 s[90:91], -1, 0
	s_cmp_lg_u32 s10, 1
	s_cselect_b64 s[60:61], -1, 0
	s_cmp_eq_u32 s10, 1
	v_readlane_b32 s4, v254, 44
	v_readlane_b32 s5, v254, 48
	s_cselect_b32 s51, 0, 64
	s_cselect_b32 s4, s5, s4
	s_cmp_eq_u32 s10, 0
	v_readlane_b32 s5, v254, 47
	s_cselect_b32 s70, s5, s4
	s_cselect_b32 s51, 0x58, s51
	s_cmp_lg_u32 s10, 2
	v_writelane_b32 v255, s10, 6
	s_cselect_b64 s[52:53], -1, 0
	s_mov_b32 s71, s59
	s_mov_b32 s7, 0
	s_branch .LBB0_419

.LBB0_519:
	s_and_b64 vcc, exec, s[10:11]
	s_cbranch_vccz .LBB0_614
	s_and_b64 vcc, exec, s[90:91]
	s_cbranch_vccnz .Lmx_diff_go
	s_cmp_lt_i32 s76, 40
	s_cbranch_scc1 .Lmx_diff_go
	s_cmp_lt_i32 s76, 64
	s_cbranch_scc1 .Lmx_to_sb
	s_sub_i32 s76, s76, 24
	s_branch .Lmx_diff_go
.Lmx_to_sb:
	s_sub_i32 s76, s76, 40
	s_branch .Lmx_sb_go
